# NORM row loop software-pipelined across trips: next trip's first-body loads issued right after the first body's stores (overlapping the second body's math), counted waits raised by 8
# baseline (speedup 1.0000x reference)
; __device__ __forceinline__ void norm_phase(const Params& p, int layer) {
;     ...
;     for (int r0 = gw * RPW; r0 < MTOK; r0 += ngw * RPW) {
;         const float* mb = mod + (r0 >> 13) * 3072;
;         f32x4 gs[4], sh[4];
; #pragma unroll
;         for (int j = 0; j < 4; ++j) { const int col = 4 * lane + 256 * j; gs[j] = *(const f32x4*)(g + col) * (*(const f32x4*)(mb + 1024 + col) + 1.0f); sh[j] = *(const f32x4*)(mb + col); }
;         for (int rr = 0; rr < RPW; rr += 2) {
;             const int row = r0 + rr;
;             const f32x4* xa = (const f32x4*)(src + (size_t)row * DM) + lane; const f32x4* xb = xa + DM / 4;
;             f32x4 va[4], vb[4]; float sa = 0.f, sb = 0.f;
; #pragma unroll
;             for (int j = 0; j < 4; ++j) { va[j] = __builtin_nontemporal_load(xa + 64 * j); vb[j] = __builtin_nontemporal_load(xb + 64 * j); }
; #pragma unroll
;             for (int j = 0; j < 4; ++j) { sa += (va[j][0] * va[j][0] + va[j][1] * va[j][1]) + (va[j][2] * va[j][2] + va[j][3] * va[j][3]); sb += (vb[j][0] * vb[j][0] + vb[j][1] * vb[j][1]) + (vb[j][2] * vb[j][2] + vb[j][3] * vb[j][3]); }
.LBB0_414:
	v_ashrrev_i32_e32 v2, 13, v18
	v_mul_i32_i24_e32 v2, 0xc00, v2
	v_ashrrev_i32_e32 v3, 31, v2
	v_lshl_add_u64 v[2:3], v[2:3], 2, s[26:27]
	v_lshl_add_u64 v[4:5], v[2:3], 0, s[98:99]
	v_mov_b32_e32 v29, v0
	v_lshl_add_u64 v[6:7], v[4:5], 0, v[28:29]
	v_mov_b32_e32 v31, v0
	v_mov_b32_e32 v33, v0
	global_load_dwordx4 v[6:9], v[6:7], off
	s_nop 0
	global_load_dwordx4 v[10:13], v[20:21], off
	v_lshl_add_u64 v[14:15], v[4:5], 0, v[30:31]
	v_mov_b32_e32 v35, v0
	v_lshl_add_u64 v[36:37], v[4:5], 0, v[32:33]
	global_load_dwordx4 v[14:17], v[14:15], off
	s_nop 0
	global_load_dwordx4 v[42:45], v[20:21], off offset:1024
	global_load_dwordx4 v[46:49], v[36:37], off
	v_lshl_add_u64 v[4:5], v[4:5], 0, v[34:35]
	global_load_dwordx4 v[50:53], v[4:5], off
	global_load_dwordx4 v[54:57], v[20:21], off offset:2048
	v_lshl_add_u64 v[62:63], v[2:3], 0, v[28:29]
	global_load_dwordx4 v[58:61], v[20:21], off offset:3072
	global_load_dwordx4 v[2:5], v[62:63], off
	s_mov_b32 s4, -2
	s_waitcnt vmcnt(0)
	v_pk_add_f32 v[8:9], v[8:9], 1.0 op_sel_hi:[1,0]
	v_pk_add_f32 v[6:7], v[6:7], 1.0 op_sel_hi:[1,0]
	v_pk_mul_f32 v[36:37], v[12:13], v[8:9]
	v_pk_mul_f32 v[38:39], v[10:11], v[6:7]
	v_pk_add_f32 v[10:11], v[16:17], 1.0 op_sel_hi:[1,0]
	v_pk_add_f32 v[12:13], v[14:15], 1.0 op_sel_hi:[1,0]
	v_pk_mul_f32 v[40:41], v[44:45], v[10:11]
	v_pk_mul_f32 v[42:43], v[42:43], v[12:13]
	v_pk_add_f32 v[10:11], v[48:49], 1.0 op_sel_hi:[1,0]
	v_pk_add_f32 v[12:13], v[46:47], 1.0 op_sel_hi:[1,0]
	global_load_dwordx4 v[6:9], v[62:63], off offset:3072
	v_pk_mul_f32 v[44:45], v[56:57], v[10:11]
	v_pk_mul_f32 v[46:47], v[54:55], v[12:13]
	global_load_dwordx4 v[10:13], v[62:63], off offset:1024
	global_load_dwordx4 v[14:17], v[62:63], off offset:2048
	v_pk_add_f32 v[48:49], v[52:53], 1.0 op_sel_hi:[1,0]
	v_pk_add_f32 v[50:51], v[50:51], 1.0 op_sel_hi:[1,0]
	v_pk_mul_f32 v[48:49], v[60:61], v[48:49]
	v_pk_mul_f32 v[50:51], v[58:59], v[50:51]
	v_mov_b64_e32 v[52:53], v[26:27]
	v_mov_b64_e32 v[54:55], v[24:25]
	global_load_dwordx4 v[56:59], v[54:55], off offset:-4096 nt
	global_load_dwordx4 v[60:63], v[54:55], off nt
	global_load_dwordx4 v[64:67], v[54:55], off offset:-3072 nt
	global_load_dwordx4 v[70:73], v[54:55], off offset:1024 nt
	global_load_dwordx4 v[102:105], v[54:55], off offset:-2048 nt
	global_load_dwordx4 v[106:109], v[54:55], off offset:-1024 nt
	global_load_dwordx4 v[110:113], v[54:55], off offset:2048 nt
	global_load_dwordx4 v[114:117], v[54:55], off offset:3072 nt
	global_load_dwordx4 v[118:121], v[54:55], off offset:-4096 nt
	global_load_dwordx4 v[122:125], v[54:55], off nt
	global_load_dwordx4 v[126:129], v[54:55], off offset:-3072 nt
	global_load_dwordx4 v[130:133], v[54:55], off offset:1024 nt
	global_load_dwordx4 v[134:137], v[54:55], off offset:-2048 nt
	global_load_dwordx4 v[138:141], v[54:55], off offset:-1024 nt
	global_load_dwordx4 v[142:145], v[54:55], off offset:2048 nt
	global_load_dwordx4 v[146:149], v[54:55], off offset:3072 nt
.LBB0_415:
	v_lshl_add_u64 v[150:151], v[54:55], 0, s[6:7]
	global_load_dwordx4 v[118:121], v[150:151], off offset:-4096 nt
	global_load_dwordx4 v[122:125], v[150:151], off nt
	global_load_dwordx4 v[126:129], v[150:151], off offset:-3072 nt
	global_load_dwordx4 v[130:133], v[150:151], off offset:1024 nt
	global_load_dwordx4 v[134:137], v[150:151], off offset:-2048 nt
	global_load_dwordx4 v[138:141], v[150:151], off offset:-1024 nt
	global_load_dwordx4 v[142:145], v[150:151], off offset:2048 nt
	global_load_dwordx4 v[146:149], v[150:151], off offset:3072 nt
	s_waitcnt vmcnt(23)
	v_pk_mul_f32 v[68:69], v[58:59], v[58:59]
	v_pk_mul_f32 v[74:75], v[56:57], v[56:57]
	s_waitcnt vmcnt(22)
	v_pk_mul_f32 v[76:77], v[62:63], v[62:63]
	v_pk_mov_b32 v[78:79], v[74:75], v[68:69] op_sel:[1,0]
	v_mov_b32_e32 v75, v69
	v_pk_mul_f32 v[68:69], v[60:61], v[60:61]
	s_waitcnt vmcnt(21)
	v_pk_mul_f32 v[82:83], v[64:65], v[64:65]
	v_pk_mov_b32 v[80:81], v[68:69], v[76:77] op_sel:[1,0]
	v_mov_b32_e32 v69, v77
	v_pk_mul_f32 v[76:77], v[66:67], v[66:67]
	s_waitcnt vmcnt(20)
	v_pk_mul_f32 v[86:87], v[70:71], v[70:71]
	v_pk_mov_b32 v[84:85], v[82:83], v[76:77] op_sel:[1,0]
	v_mov_b32_e32 v83, v77
	v_pk_mul_f32 v[76:77], v[72:73], v[72:73]
	v_pk_add_f32 v[90:91], v[78:79], v[74:75]
	v_pk_mov_b32 v[88:89], v[86:87], v[76:77] op_sel:[1,0]
	v_mov_b32_e32 v87, v77
	v_pk_add_f32 v[68:69], v[80:81], v[68:69]
	v_pk_add_f32 v[92:93], v[84:85], v[82:83]
	v_pk_add_f32 v[94:95], v[88:89], v[86:87]
	v_pk_add_f32 v[90:91], v[90:91], v[90:91] op_sel:[0,1] op_sel_hi:[1,0]
	v_pk_add_f32 v[92:93], v[92:93], v[92:93] op_sel:[0,1] op_sel_hi:[1,0]
	v_pk_add_f32 v[68:69], v[68:69], v[68:69] op_sel:[0,1] op_sel_hi:[1,0]
	s_waitcnt vmcnt(19)
	v_mul_f32_e32 v82, v103, v103
	v_mul_f32_e32 v84, v105, v105
	v_pk_fma_f32 v[82:83], v[102:103], v[102:103], v[82:83] op_sel_hi:[1,1,0]
	v_pk_fma_f32 v[84:85], v[104:105], v[104:105], v[84:85] op_sel_hi:[1,1,0]
	s_waitcnt vmcnt(18)
	v_mul_f32_e32 v83, v108, v108
	v_mul_f32_e32 v85, v109, v109
	v_pk_add_f32 v[96:97], v[82:83], v[84:85]
	v_mul_f32_e32 v91, v106, v106
	v_mul_f32_e32 v93, v107, v107
	v_pk_add_f32 v[90:91], v[90:91], v[92:93]
	v_pk_add_f32 v[92:93], v[94:95], v[94:95] op_sel:[0,1] op_sel_hi:[1,0]
	v_pk_add_f32 v[90:91], v[90:91], v[96:97]
	v_lshl_add_u64 v[54:55], v[54:55], 0, s[6:7]
	s_waitcnt vmcnt(17)
	v_mul_f32_e32 v98, v111, v111
	v_mul_f32_e32 v100, v113, v113
	v_pk_fma_f32 v[98:99], v[110:111], v[110:111], v[98:99] op_sel_hi:[1,1,0]
	v_pk_fma_f32 v[100:101], v[112:113], v[112:113], v[100:101] op_sel_hi:[1,1,0]
	s_waitcnt vmcnt(16)
; __device__ __forceinline__ unsigned pk_bf16(float lo, float hi) { const f32x2 v = {lo, hi}; const bf16v2 b = __builtin_convertvector(v, bf16v2); return __builtin_bit_cast(unsigned, b); }
; template <int X> __device__ __forceinline__ float swz_xor(float v) { return __int_as_float(__builtin_amdgcn_ds_swizzle(__float_as_int(v), 0x1f | (X << 10))); }
; __device__ __forceinline__ float xor32(float v, int x32a) { return __int_as_float(__builtin_amdgcn_ds_bpermute(x32a, __float_as_int(v))); }
; __device__ __forceinline__ float wave_sum(float v, int x32a) {
;     v += swz_xor<1>(v); v += swz_xor<2>(v); v += swz_xor<4>(v); v += swz_xor<8>(v); v += swz_xor<16>(v); v += xor32(v, x32a);
;     return v;
; __device__ __forceinline__ void norm_phase(const Params& p, int layer) {
;     ...
;             for (int j = 0; j < 4; ++j) { sa += (va[j][0] * va[j][0] + va[j][1] * va[j][1]) + (va[j][2] * va[j][2] + va[j][3] * va[j][3]); sb += (vb[j][0] * vb[j][0] + vb[j][1] * vb[j][1]) + (vb[j][2] * vb[j][2] + vb[j][3] * vb[j][3]); }
;             const float ra = rsqrtf(wave_sum(sa, x32a) * (1.0f / DM) + 1e-6f), rb = rsqrtf(wave_sum(sb, x32a) * (1.0f / DM) + 1e-6f);
; #pragma unroll
;             for (int j = 0; j < 4; ++j) { const int col = 4 * lane + 256 * j;
;                 const f32x4 ya = (va[j] * ra) * gs[j] + sh[j], yb = (vb[j] * rb) * gs[j] + sh[j];
;                 u32x2 wa, wb; wa.x = pk_bf16(ya[0], ya[1]); wa.y = pk_bf16(ya[2], ya[3]); wb.x = pk_bf16(yb[0], yb[1]); wb.y = pk_bf16(yb[2], yb[3]);
;                 *(u32x2*)(H + (size_t)row * DM + col) = wa; *(u32x2*)(H + (size_t)(row + 1) * DM + col) = wb; }
	v_mul_f32_e32 v99, v116, v116
	v_mul_f32_e32 v101, v117, v117
	v_mul_f32_e32 v69, v114, v114
	v_mul_f32_e32 v93, v115, v115
	v_pk_add_f32 v[98:99], v[98:99], v[100:101]
	v_pk_add_f32 v[68:69], v[68:69], v[92:93]
	v_mov_b32_e32 v93, v90
	v_pk_add_f32 v[68:69], v[68:69], v[98:99]
	s_nop 0
	v_mov_b32_e32 v92, v68
	v_mov_b32_e32 v90, v69
	v_pk_add_f32 v[68:69], v[92:93], v[90:91]
	s_nop 1
	v_add_f32_dpp v68, v68, v68 quad_perm:[1,0,3,2] row_mask:0xf bank_mask:0xf
	v_add_f32_dpp v69, v69, v69 quad_perm:[1,0,3,2] row_mask:0xf bank_mask:0xf
	s_nop 0
	v_add_f32_dpp v68, v68, v68 quad_perm:[2,3,0,1] row_mask:0xf bank_mask:0xf
	v_add_f32_dpp v69, v69, v69 quad_perm:[2,3,0,1] row_mask:0xf bank_mask:0xf
	s_nop 0
	v_add_f32_dpp v68, v68, v68 row_half_mirror row_mask:0xf bank_mask:0xf
	v_add_f32_dpp v69, v69, v69 row_half_mirror row_mask:0xf bank_mask:0xf
	s_nop 0
	v_add_f32_dpp v68, v68, v68 row_mirror row_mask:0xf bank_mask:0xf
	v_add_f32_dpp v69, v69, v69 row_mirror row_mask:0xf bank_mask:0xf
	s_nop 0
	v_mov_b32_e32 v90, v68
	v_mov_b32_e32 v91, v69
	s_nop 1
	v_permlane16_swap_b32_e32 v68, v90
	v_permlane16_swap_b32_e32 v69, v91
	v_add_f32_e32 v68, v68, v90
	v_add_f32_e32 v69, v69, v91
	v_mov_b32_e32 v90, v68
	v_mov_b32_e32 v91, v69
	s_nop 1
	v_permlane32_swap_b32_e32 v68, v90
	v_permlane32_swap_b32_e32 v69, v91
	v_add_f32_e32 v68, v68, v90
	v_add_f32_e32 v69, v69, v91
	s_nop 0
	v_pk_fma_f32 v[90:91], v[68:69], s[8:9], v[206:207] op_sel_hi:[1,0,0]
	s_nop 0
	v_mul_f32_e32 v19, 0x4b800000, v91
	v_cmp_gt_f32_e32 vcc, s82, v91
	s_nop 1
	v_cndmask_b32_e32 v19, v91, v19, vcc
	v_rsq_f32_e32 v19, v19
	s_nop 0
	v_mul_f32_e32 v29, 0x45800000, v19
	v_cndmask_b32_e32 v68, v19, v29, vcc
	v_mul_f32_e32 v19, 0x4b800000, v90
	v_cmp_gt_f32_e32 vcc, s82, v90
	v_pk_mul_f32 v[56:57], v[56:57], v[68:69] op_sel_hi:[1,0]
	v_pk_mul_f32 v[58:59], v[58:59], v[68:69] op_sel_hi:[1,0]
	v_cndmask_b32_e32 v19, v90, v19, vcc
	v_rsq_f32_e32 v19, v19
	v_pk_mul_f32 v[94:95], v[102:103], v[68:69] op_sel_hi:[1,0]
	v_pk_fma_f32 v[58:59], v[36:37], v[58:59], v[4:5]
	v_pk_fma_f32 v[56:57], v[38:39], v[56:57], v[2:3]
	v_mul_f32_e32 v29, 0x45800000, v19
	v_cndmask_b32_e32 v74, v19, v29, vcc
	v_pk_mul_f32 v[60:61], v[60:61], v[74:75] op_sel_hi:[1,0]
	v_pk_mul_f32 v[62:63], v[62:63], v[74:75] op_sel_hi:[1,0]
	v_pk_mul_f32 v[64:65], v[64:65], v[68:69] op_sel_hi:[1,0]
	v_pk_mul_f32 v[92:93], v[66:67], v[68:69] op_sel_hi:[1,0]
	v_cvt_pk_bf16_f32 v56, v56, v57
	v_cvt_pk_bf16_f32 v57, v58, v59
	v_pk_fma_f32 v[62:63], v[36:37], v[62:63], v[4:5]
	v_pk_fma_f32 v[58:59], v[38:39], v[60:61], v[2:3]
	v_pk_mul_f32 v[96:97], v[104:105], v[68:69] op_sel_hi:[1,0]
	v_pk_mul_f32 v[66:67], v[106:107], v[68:69] op_sel_hi:[1,0]
	v_pk_mul_f32 v[68:69], v[108:109], v[68:69] op_sel_hi:[1,0]
	v_pk_mul_f32 v[78:79], v[70:71], v[74:75] op_sel_hi:[1,0]
	v_pk_mul_f32 v[80:81], v[72:73], v[74:75] op_sel_hi:[1,0]
	v_cvt_pk_bf16_f32 v58, v58, v59
	v_cvt_pk_bf16_f32 v59, v62, v63
	v_pk_fma_f32 v[62:63], v[40:41], v[92:93], v[12:13]
	v_pk_fma_f32 v[60:61], v[42:43], v[64:65], v[10:11]
	v_pk_fma_f32 v[64:65], v[40:41], v[80:81], v[12:13]
	v_cvt_pk_bf16_f32 v60, v60, v61
	v_cvt_pk_bf16_f32 v61, v62, v63
	v_pk_fma_f32 v[62:63], v[42:43], v[78:79], v[10:11]
	v_pk_fma_f32 v[78:79], v[44:45], v[96:97], v[16:17]
	v_cvt_pk_bf16_f32 v62, v62, v63
	v_cvt_pk_bf16_f32 v63, v64, v65
	v_pk_fma_f32 v[64:65], v[46:47], v[94:95], v[14:15]
	v_pk_mul_f32 v[72:73], v[110:111], v[74:75] op_sel_hi:[1,0]
	v_cvt_pk_bf16_f32 v64, v64, v65
	v_cvt_pk_bf16_f32 v65, v78, v79
	v_add3_u32 v78, v18, s4, 3
	v_pk_mul_f32 v[76:77], v[112:113], v[74:75] op_sel_hi:[1,0]
	v_pk_mul_f32 v[70:71], v[114:115], v[74:75] op_sel_hi:[1,0]
	v_pk_mul_f32 v[74:75], v[116:117], v[74:75] op_sel_hi:[1,0]
	v_ashrrev_i32_e32 v79, 31, v78
	s_add_i32 s4, s4, 2
	v_lshlrev_b64 v[78:79], 11, v[78:79]
	v_pk_fma_f32 v[76:77], v[44:45], v[76:77], v[16:17]
	v_pk_fma_f32 v[72:73], v[46:47], v[72:73], v[14:15]
	v_pk_fma_f32 v[68:69], v[48:49], v[68:69], v[8:9]
	v_pk_fma_f32 v[66:67], v[50:51], v[66:67], v[6:7]
	v_pk_fma_f32 v[74:75], v[48:49], v[74:75], v[8:9]
	v_pk_fma_f32 v[70:71], v[50:51], v[70:71], v[6:7]
	s_cmp_gt_u32 s4, 13
	v_lshl_add_u64 v[78:79], v[22:23], 0, v[78:79]
	v_cvt_pk_bf16_f32 v72, v72, v73
	v_cvt_pk_bf16_f32 v73, v76, v77
	v_cvt_pk_bf16_f32 v66, v66, v67
	v_cvt_pk_bf16_f32 v67, v68, v69
	v_cvt_pk_bf16_f32 v68, v70, v71
	v_cvt_pk_bf16_f32 v69, v74, v75
	global_store_dwordx2 v[52:53], v[56:57], off offset:-1024
	global_store_dwordx2 v[78:79], v[58:59], off
	global_store_dwordx2 v[52:53], v[60:61], off offset:-512
	global_store_dwordx2 v[78:79], v[62:63], off offset:512
	global_store_dwordx2 v[52:53], v[64:65], off
	global_store_dwordx2 v[78:79], v[72:73], off offset:1024
	global_store_dwordx2 v[52:53], v[66:67], off offset:512
	global_store_dwordx2 v[78:79], v[68:69], off offset:1536
	s_cmp_eq_u32 s4, 12
	s_cbranch_scc1 .Lnp_last
	v_lshl_add_u64 v[152:153], v[54:55], 0, s[6:7]
	s_branch .Lnp_go
.Lnp_last:
	v_mov_b64_e32 v[152:153], v[54:55]
; __device__ __forceinline__ void norm_phase(const Params& p, int layer) {
;     ...
;             const f32x4* xa = (const f32x4*)(src + (size_t)row * DM) + lane; const f32x4* xb = xa + DM / 4;
;             f32x4 va[4], vb[4]; float sa = 0.f, sb = 0.f;
; #pragma unroll
;             for (int j = 0; j < 4; ++j) { va[j] = __builtin_nontemporal_load(xa + 64 * j); vb[j] = __builtin_nontemporal_load(xb + 64 * j); }
; #pragma unroll
;             for (int j = 0; j < 4; ++j) { sa += (va[j][0] * va[j][0] + va[j][1] * va[j][1]) + (va[j][2] * va[j][2] + va[j][3] * va[j][3]); sb += (vb[j][0] * vb[j][0] + vb[j][1] * vb[j][1]) + (vb[j][2] * vb[j][2] + vb[j][3] * vb[j][3]); }
;             const float ra = rsqrtf(wave_sum(sa, x32a) * (1.0f / DM) + 1e-6f), rb = rsqrtf(wave_sum(sb, x32a) * (1.0f / DM) + 1e-6f);
.Lnp_go:
	global_load_dwordx4 v[56:59], v[152:153], off offset:-4096 nt
	global_load_dwordx4 v[60:63], v[152:153], off nt
	global_load_dwordx4 v[64:67], v[152:153], off offset:-3072 nt
	global_load_dwordx4 v[70:73], v[152:153], off offset:1024 nt
	global_load_dwordx4 v[102:105], v[152:153], off offset:-2048 nt
	global_load_dwordx4 v[106:109], v[152:153], off offset:-1024 nt
	global_load_dwordx4 v[110:113], v[152:153], off offset:2048 nt
	global_load_dwordx4 v[114:117], v[152:153], off offset:3072 nt
	v_lshl_add_u64 v[52:53], v[52:53], 0, s[98:99]
	s_waitcnt vmcnt(23)
	v_pk_mul_f32 v[68:69], v[120:121], v[120:121]
	v_pk_mul_f32 v[74:75], v[118:119], v[118:119]
	s_waitcnt vmcnt(22)
	v_pk_mul_f32 v[76:77], v[124:125], v[124:125]
	v_pk_mov_b32 v[78:79], v[74:75], v[68:69] op_sel:[1,0]
	v_mov_b32_e32 v75, v69
	v_pk_mul_f32 v[68:69], v[122:123], v[122:123]
	s_waitcnt vmcnt(21)
	v_pk_mul_f32 v[82:83], v[126:127], v[126:127]
	v_pk_mov_b32 v[80:81], v[68:69], v[76:77] op_sel:[1,0]
	v_mov_b32_e32 v69, v77
	v_pk_mul_f32 v[76:77], v[128:129], v[128:129]
	s_waitcnt vmcnt(20)
	v_pk_mul_f32 v[86:87], v[130:131], v[130:131]
	v_pk_mov_b32 v[84:85], v[82:83], v[76:77] op_sel:[1,0]
	v_mov_b32_e32 v83, v77
	v_pk_mul_f32 v[76:77], v[132:133], v[132:133]
	v_pk_add_f32 v[90:91], v[78:79], v[74:75]
	v_pk_mov_b32 v[88:89], v[86:87], v[76:77] op_sel:[1,0]
	v_mov_b32_e32 v87, v77
	v_pk_add_f32 v[68:69], v[80:81], v[68:69]
	v_pk_add_f32 v[92:93], v[84:85], v[82:83]
	v_pk_add_f32 v[94:95], v[88:89], v[86:87]
	v_pk_add_f32 v[90:91], v[90:91], v[90:91] op_sel:[0,1] op_sel_hi:[1,0]
	v_pk_add_f32 v[92:93], v[92:93], v[92:93] op_sel:[0,1] op_sel_hi:[1,0]
	v_pk_add_f32 v[68:69], v[68:69], v[68:69] op_sel:[0,1] op_sel_hi:[1,0]
	s_waitcnt vmcnt(19)
	v_mul_f32_e32 v82, v135, v135
	v_mul_f32_e32 v84, v137, v137
	v_pk_fma_f32 v[82:83], v[134:135], v[134:135], v[82:83] op_sel_hi:[1,1,0]
	v_pk_fma_f32 v[84:85], v[136:137], v[136:137], v[84:85] op_sel_hi:[1,1,0]
	s_waitcnt vmcnt(18)
	v_mul_f32_e32 v83, v140, v140
	v_mul_f32_e32 v85, v141, v141
	v_pk_add_f32 v[96:97], v[82:83], v[84:85]
	v_mul_f32_e32 v91, v138, v138
	v_mul_f32_e32 v93, v139, v139
	v_pk_add_f32 v[90:91], v[90:91], v[92:93]
	v_pk_add_f32 v[92:93], v[94:95], v[94:95] op_sel:[0,1] op_sel_hi:[1,0]
	v_pk_add_f32 v[90:91], v[90:91], v[96:97]
	v_lshl_add_u64 v[54:55], v[54:55], 0, s[6:7]
	s_waitcnt vmcnt(17)
	v_mul_f32_e32 v98, v143, v143
	v_mul_f32_e32 v100, v145, v145
	v_pk_fma_f32 v[98:99], v[142:143], v[142:143], v[98:99] op_sel_hi:[1,1,0]
	v_pk_fma_f32 v[100:101], v[144:145], v[144:145], v[100:101] op_sel_hi:[1,1,0]
	s_waitcnt vmcnt(16)
; __device__ __forceinline__ unsigned pk_bf16(float lo, float hi) { const f32x2 v = {lo, hi}; const bf16v2 b = __builtin_convertvector(v, bf16v2); return __builtin_bit_cast(unsigned, b); }
; template <int X> __device__ __forceinline__ float swz_xor(float v) { return __int_as_float(__builtin_amdgcn_ds_swizzle(__float_as_int(v), 0x1f | (X << 10))); }
; __device__ __forceinline__ float xor32(float v, int x32a) { return __int_as_float(__builtin_amdgcn_ds_bpermute(x32a, __float_as_int(v))); }
; __device__ __forceinline__ float wave_sum(float v, int x32a) {
;     v += swz_xor<1>(v); v += swz_xor<2>(v); v += swz_xor<4>(v); v += swz_xor<8>(v); v += swz_xor<16>(v); v += xor32(v, x32a);
;     return v;
; __device__ __forceinline__ void norm_phase(const Params& p, int layer) {
;     ...
;             for (int j = 0; j < 4; ++j) { sa += (va[j][0] * va[j][0] + va[j][1] * va[j][1]) + (va[j][2] * va[j][2] + va[j][3] * va[j][3]); sb += (vb[j][0] * vb[j][0] + vb[j][1] * vb[j][1]) + (vb[j][2] * vb[j][2] + vb[j][3] * vb[j][3]); }
;             const float ra = rsqrtf(wave_sum(sa, x32a) * (1.0f / DM) + 1e-6f), rb = rsqrtf(wave_sum(sb, x32a) * (1.0f / DM) + 1e-6f);
; #pragma unroll
;             for (int j = 0; j < 4; ++j) { const int col = 4 * lane + 256 * j;
;                 const f32x4 ya = (va[j] * ra) * gs[j] + sh[j], yb = (vb[j] * rb) * gs[j] + sh[j];
;                 u32x2 wa, wb; wa.x = pk_bf16(ya[0], ya[1]); wa.y = pk_bf16(ya[2], ya[3]); wb.x = pk_bf16(yb[0], yb[1]); wb.y = pk_bf16(yb[2], yb[3]);
;                 *(u32x2*)(H + (size_t)row * DM + col) = wa; *(u32x2*)(H + (size_t)(row + 1) * DM + col) = wb; }
;         }
;     }
	v_mul_f32_e32 v99, v148, v148
	v_mul_f32_e32 v101, v149, v149
	v_mul_f32_e32 v69, v146, v146
	v_mul_f32_e32 v93, v147, v147
	v_pk_add_f32 v[98:99], v[98:99], v[100:101]
	v_pk_add_f32 v[68:69], v[68:69], v[92:93]
	v_mov_b32_e32 v93, v90
	v_pk_add_f32 v[68:69], v[68:69], v[98:99]
	s_nop 0
	v_mov_b32_e32 v92, v68
	v_mov_b32_e32 v90, v69
	v_pk_add_f32 v[68:69], v[92:93], v[90:91]
	s_nop 1
	v_add_f32_dpp v68, v68, v68 quad_perm:[1,0,3,2] row_mask:0xf bank_mask:0xf
	v_add_f32_dpp v69, v69, v69 quad_perm:[1,0,3,2] row_mask:0xf bank_mask:0xf
	s_nop 0
	v_add_f32_dpp v68, v68, v68 quad_perm:[2,3,0,1] row_mask:0xf bank_mask:0xf
	v_add_f32_dpp v69, v69, v69 quad_perm:[2,3,0,1] row_mask:0xf bank_mask:0xf
	s_nop 0
	v_add_f32_dpp v68, v68, v68 row_half_mirror row_mask:0xf bank_mask:0xf
	v_add_f32_dpp v69, v69, v69 row_half_mirror row_mask:0xf bank_mask:0xf
	s_nop 0
	v_add_f32_dpp v68, v68, v68 row_mirror row_mask:0xf bank_mask:0xf
	v_add_f32_dpp v69, v69, v69 row_mirror row_mask:0xf bank_mask:0xf
	s_nop 0
	v_mov_b32_e32 v90, v68
	v_mov_b32_e32 v91, v69
	s_nop 1
	v_permlane16_swap_b32_e32 v68, v90
	v_permlane16_swap_b32_e32 v69, v91
	v_add_f32_e32 v68, v68, v90
	v_add_f32_e32 v69, v69, v91
	v_mov_b32_e32 v90, v68
	v_mov_b32_e32 v91, v69
	s_nop 1
	v_permlane32_swap_b32_e32 v68, v90
	v_permlane32_swap_b32_e32 v69, v91
	v_add_f32_e32 v68, v68, v90
	v_add_f32_e32 v69, v69, v91
	s_nop 0
	v_pk_fma_f32 v[90:91], v[68:69], s[8:9], v[206:207] op_sel_hi:[1,0,0]
	s_nop 0
	v_mul_f32_e32 v19, 0x4b800000, v91
	v_cmp_gt_f32_e32 vcc, s82, v91
	s_nop 1
	v_cndmask_b32_e32 v19, v91, v19, vcc
	v_rsq_f32_e32 v19, v19
	s_nop 0
	v_mul_f32_e32 v29, 0x45800000, v19
	v_cndmask_b32_e32 v68, v19, v29, vcc
	v_mul_f32_e32 v19, 0x4b800000, v90
	v_cmp_gt_f32_e32 vcc, s82, v90
	v_pk_mul_f32 v[118:119], v[118:119], v[68:69] op_sel_hi:[1,0]
	v_pk_mul_f32 v[120:121], v[120:121], v[68:69] op_sel_hi:[1,0]
	v_cndmask_b32_e32 v19, v90, v19, vcc
	v_rsq_f32_e32 v19, v19
	v_pk_mul_f32 v[94:95], v[134:135], v[68:69] op_sel_hi:[1,0]
	v_pk_fma_f32 v[120:121], v[36:37], v[120:121], v[4:5]
	v_pk_fma_f32 v[118:119], v[38:39], v[118:119], v[2:3]
	v_mul_f32_e32 v29, 0x45800000, v19
	v_cndmask_b32_e32 v74, v19, v29, vcc
	v_pk_mul_f32 v[122:123], v[122:123], v[74:75] op_sel_hi:[1,0]
	v_pk_mul_f32 v[124:125], v[124:125], v[74:75] op_sel_hi:[1,0]
	v_pk_mul_f32 v[126:127], v[126:127], v[68:69] op_sel_hi:[1,0]
	v_pk_mul_f32 v[92:93], v[128:129], v[68:69] op_sel_hi:[1,0]
	v_cvt_pk_bf16_f32 v118, v118, v119
	v_cvt_pk_bf16_f32 v119, v120, v121
	v_pk_fma_f32 v[124:125], v[36:37], v[124:125], v[4:5]
	v_pk_fma_f32 v[120:121], v[38:39], v[122:123], v[2:3]
	v_pk_mul_f32 v[96:97], v[136:137], v[68:69] op_sel_hi:[1,0]
	v_pk_mul_f32 v[128:129], v[138:139], v[68:69] op_sel_hi:[1,0]
	v_pk_mul_f32 v[68:69], v[140:141], v[68:69] op_sel_hi:[1,0]
	v_pk_mul_f32 v[78:79], v[130:131], v[74:75] op_sel_hi:[1,0]
	v_pk_mul_f32 v[80:81], v[132:133], v[74:75] op_sel_hi:[1,0]
	v_cvt_pk_bf16_f32 v120, v120, v121
	v_cvt_pk_bf16_f32 v121, v124, v125
	v_pk_fma_f32 v[124:125], v[40:41], v[92:93], v[12:13]
	v_pk_fma_f32 v[122:123], v[42:43], v[126:127], v[10:11]
	v_pk_fma_f32 v[126:127], v[40:41], v[80:81], v[12:13]
	v_cvt_pk_bf16_f32 v122, v122, v123
	v_cvt_pk_bf16_f32 v123, v124, v125
	v_pk_fma_f32 v[124:125], v[42:43], v[78:79], v[10:11]
	v_pk_fma_f32 v[78:79], v[44:45], v[96:97], v[16:17]
	v_cvt_pk_bf16_f32 v124, v124, v125
	v_cvt_pk_bf16_f32 v125, v126, v127
	v_pk_fma_f32 v[126:127], v[46:47], v[94:95], v[14:15]
	v_pk_mul_f32 v[132:133], v[142:143], v[74:75] op_sel_hi:[1,0]
	v_cvt_pk_bf16_f32 v126, v126, v127
	v_cvt_pk_bf16_f32 v127, v78, v79
	v_add3_u32 v78, v18, s4, 3
	v_pk_mul_f32 v[76:77], v[144:145], v[74:75] op_sel_hi:[1,0]
	v_pk_mul_f32 v[130:131], v[146:147], v[74:75] op_sel_hi:[1,0]
	v_pk_mul_f32 v[74:75], v[148:149], v[74:75] op_sel_hi:[1,0]
	v_ashrrev_i32_e32 v79, 31, v78
	s_add_i32 s4, s4, 2
	v_lshlrev_b64 v[78:79], 11, v[78:79]
	v_pk_fma_f32 v[76:77], v[44:45], v[76:77], v[16:17]
	v_pk_fma_f32 v[132:133], v[46:47], v[132:133], v[14:15]
	v_pk_fma_f32 v[68:69], v[48:49], v[68:69], v[8:9]
	v_pk_fma_f32 v[128:129], v[50:51], v[128:129], v[6:7]
	v_pk_fma_f32 v[74:75], v[48:49], v[74:75], v[8:9]
	v_pk_fma_f32 v[130:131], v[50:51], v[130:131], v[6:7]
	s_cmp_gt_u32 s4, 13
	v_lshl_add_u64 v[78:79], v[22:23], 0, v[78:79]
	v_cvt_pk_bf16_f32 v132, v132, v133
	v_cvt_pk_bf16_f32 v133, v76, v77
	v_cvt_pk_bf16_f32 v128, v128, v129
	v_cvt_pk_bf16_f32 v129, v68, v69
	v_cvt_pk_bf16_f32 v68, v130, v131
	v_cvt_pk_bf16_f32 v69, v74, v75
	global_store_dwordx2 v[52:53], v[118:119], off offset:-1024
	global_store_dwordx2 v[78:79], v[120:121], off
	global_store_dwordx2 v[52:53], v[122:123], off offset:-512
	global_store_dwordx2 v[78:79], v[124:125], off offset:512
	global_store_dwordx2 v[52:53], v[126:127], off
	global_store_dwordx2 v[78:79], v[132:133], off offset:1024
	global_store_dwordx2 v[52:53], v[128:129], off offset:512
	global_store_dwordx2 v[78:79], v[68:69], off offset:1536
	v_lshl_add_u64 v[52:53], v[52:53], 0, s[98:99]
	s_cbranch_scc0 .LBB0_415
	v_readlane_b32 s4, v254, 62
	v_readlane_b32 s5, v254, 63
	s_nop 0
	v_add_u32_e32 v18, s4, v18
	v_readlane_b32 s4, v254, 51
	v_readlane_b32 s5, v254, 52
	v_cmp_lt_i32_e32 vcc, s2, v18
	s_or_b64 s[40:41], vcc, s[40:41]
	v_lshl_add_u64 v[24:25], v[24:25], 0, s[4:5]
	v_readlane_b32 s4, v255, 0
	v_readlane_b32 s5, v255, 1
	s_nop 1
	v_lshl_add_u64 v[26:27], v[26:27], 0, s[4:5]
	s_andn2_b64 exec, exec, s[40:41]
	s_cbranch_execnz .LBB0_414
